# attention hh0: QK chain A then chain B back to back, drain nop 10 -> 6
# speedup vs baseline: 1.0168x; 1.0030x over previous
; #define LAS __attribute__((address_space(3)))
; #define MFMA32(a, b, c) __builtin_amdgcn_mfma_f32_32x32x16_bf16((a), (b), (c), 0, 0, 0)
; #define AT_LMAX(P, MX) do { MX = fmaxf(fmaxf(P[0], P[1]), fmaxf(P[2], P[3])); \
;         _Pragma("unroll") for (int i_ = 4; i_ < 16; i_ += 4) MX = fmaxf(fmaxf(MX, P[i_]), fmaxf(fmaxf(P[i_ + 1], P[i_ + 2]), P[i_ + 3])); } while (0)
; __device__ __forceinline__ void attn_unit(LAS unsigned char* lds, const GAS bf16_t* __restrict__ QR, const GAS float* __restrict__ ssq, const GAS float* __restrict__ RT, const GAS bf16_t* __restrict__ K, const GAS bf16_t* __restrict__ Vt, GAS bf16_t* __restrict__ A2, int b, int h, int qb, int tid, i ...
;     ...
;             const LAS unsigned char* kb = sb + (32 * hh + r32s) * AT_KROW + hi * 16;
;             f32x16 pA, pB;
; #pragma unroll
;             for (int i = 0; i < 16; ++i) { pA[i] = 0.f; pB[i] = 0.f; }
; #pragma unroll
;             for (int d0 = 0; d0 < 6; ++d0) { const bf16x8 a0 = *(const LAS bf16x8*)(kb + d0 * 32); pA = MFMA32(a0, qa[d0], pA); pB = MFMA32(a0, qc[d0], pB); }
;             u32x4 pwA0, pwA1, pwB0, pwB1;
;             float mxA, mxB; AT_LMAX(pA, mxA); AT_LMAX(pB, mxB);
;             { const float oa = __shfl_xor(mxA, 32), ob = __shfl_xor(mxB, 32); mxA = fmaxf(mxA, oa); mxB = fmaxf(mxB, ob); }
;             AT_SOFTMAX(pA, mxA, mA, lA, oA0, oA1, pwA0, pwA1);
;             AT_SOFTMAX(pB, mxB, mB, lB, oB0, oB1, pwB0, pwB1);
.LBB0_139:
	s_mul_i32 s22, s1, 0x5800
	s_add_i32 s24, s22, 0
	v_add_u32_e32 v212, s24, v1
	ds_read_b128 v[66:69], v212
	ds_read_b128 v[214:217], v212 offset:32
	ds_read_b128 v[218:221], v212 offset:64
	ds_read_b128 v[222:225], v212 offset:96
	ds_read_b128 v[226:229], v212 offset:128
	ds_read_b128 v[230:233], v212 offset:160
	s_waitcnt lgkmcnt(5)
	v_mfma_f32_32x32x16_bf16 v[82:97], v[66:69], v[98:101], v[188:203]
	s_waitcnt lgkmcnt(4)
	v_mfma_f32_32x32x16_bf16 v[82:97], v[214:217], v[102:105], v[82:97]
	s_waitcnt lgkmcnt(3)
	v_mfma_f32_32x32x16_bf16 v[82:97], v[218:221], v[106:109], v[82:97]
	s_waitcnt lgkmcnt(2)
	v_mfma_f32_32x32x16_bf16 v[82:97], v[222:225], v[110:113], v[82:97]
	s_waitcnt lgkmcnt(1)
	v_mfma_f32_32x32x16_bf16 v[82:97], v[226:229], v[134:137], v[82:97]
	s_waitcnt lgkmcnt(0)
	v_mfma_f32_32x32x16_bf16 v[82:97], v[230:233], v[114:117], v[82:97]
	v_mfma_f32_32x32x16_bf16 v[66:81], v[66:69], v[118:121], v[234:249]
	v_mfma_f32_32x32x16_bf16 v[66:81], v[214:217], v[122:125], v[66:81]
	v_mfma_f32_32x32x16_bf16 v[66:81], v[218:221], v[126:129], v[66:81]
	v_mfma_f32_32x32x16_bf16 v[66:81], v[222:225], v[130:133], v[66:81]
	v_mfma_f32_32x32x16_bf16 v[66:81], v[226:229], v[138:141], v[66:81]
	v_mfma_f32_32x32x16_bf16 v[66:81], v[230:233], v[142:145], v[66:81]
	s_nop 6
	v_max_f32_e32 v210, v84, v85
	v_max3_f32 v210, v82, v83, v210
	v_max3_f32 v213, v87, v88, v89
	v_max3_f32 v214, v91, v92, v93
	v_max3_f32 v210, v210, v86, v213
	v_max3_f32 v215, v95, v96, v97
	v_max_f32_e32 v216, v68, v69
	v_max3_f32 v210, v210, v90, v214
	v_max3_f32 v216, v66, v67, v216
	v_max3_f32 v217, v71, v72, v73
	v_max3_f32 v214, v210, v94, v215
	v_max3_f32 v216, v216, v70, v217
	v_max3_f32 v217, v75, v76, v77
	ds_bpermute_b32 v215, v153, v214
	v_max3_f32 v210, v216, v74, v217
	v_max3_f32 v213, v79, v80, v81
	v_max3_f32 v210, v210, v78, v213
	ds_bpermute_b32 v213, v153, v210
	s_waitcnt lgkmcnt(1)
	v_max_f32_e32 v214, v214, v215
	v_cmp_lt_f32_e32 vcc, s100, v214
	s_cbranch_vccz .LBB0_141
	v_max_f32_e32 v215, s101, v214
	v_max_f32_e32 v214, 0, v215
	v_exp_f32_e64 v214, -v214
	v_sub_f32_e32 v188, v188, v215
	v_sub_f32_e32 v189, v189, v215
	v_sub_f32_e32 v190, v190, v215
	v_sub_f32_e32 v191, v191, v215
	v_sub_f32_e32 v192, v192, v215
	v_sub_f32_e32 v193, v193, v215
	v_sub_f32_e32 v194, v194, v215
	v_sub_f32_e32 v195, v195, v215
	v_sub_f32_e32 v196, v196, v215
	v_sub_f32_e32 v197, v197, v215
	v_sub_f32_e32 v198, v198, v215
	v_sub_f32_e32 v199, v199, v215
	v_sub_f32_e32 v200, v200, v215
	v_sub_f32_e32 v201, v201, v215
	v_sub_f32_e32 v202, v202, v215
	v_sub_f32_e32 v203, v203, v215
	v_sub_f32_e32 v82, v82, v215
	v_sub_f32_e32 v83, v83, v215
	v_sub_f32_e32 v84, v84, v215
	v_sub_f32_e32 v85, v85, v215
	v_sub_f32_e32 v86, v86, v215
	v_sub_f32_e32 v87, v87, v215
	v_sub_f32_e32 v88, v88, v215
	v_sub_f32_e32 v89, v89, v215
	v_sub_f32_e32 v90, v90, v215
	v_sub_f32_e32 v91, v91, v215
	v_sub_f32_e32 v92, v92, v215
	v_sub_f32_e32 v93, v93, v215
	v_sub_f32_e32 v94, v94, v215
	v_sub_f32_e32 v95, v95, v215
	v_sub_f32_e32 v96, v96, v215
	v_sub_f32_e32 v97, v97, v215
	v_pk_mul_f32 v[64:65], v[64:65], v[214:215] op_sel_hi:[1,0]
	v_pk_mul_f32 v[62:63], v[62:63], v[214:215] op_sel_hi:[1,0]
	v_pk_mul_f32 v[60:61], v[60:61], v[214:215] op_sel_hi:[1,0]
	v_pk_mul_f32 v[58:59], v[58:59], v[214:215] op_sel_hi:[1,0]
	v_pk_mul_f32 v[56:57], v[56:57], v[214:215] op_sel_hi:[1,0]
	v_pk_mul_f32 v[54:55], v[54:55], v[214:215] op_sel_hi:[1,0]
	v_pk_mul_f32 v[52:53], v[52:53], v[214:215] op_sel_hi:[1,0]
	v_pk_mul_f32 v[50:51], v[50:51], v[214:215] op_sel_hi:[1,0]
	v_pk_mul_f32 v[48:49], v[48:49], v[214:215] op_sel_hi:[1,0]
	v_pk_mul_f32 v[46:47], v[46:47], v[214:215] op_sel_hi:[1,0]
	v_pk_mul_f32 v[44:45], v[44:45], v[214:215] op_sel_hi:[1,0]
	v_pk_mul_f32 v[42:43], v[42:43], v[214:215] op_sel_hi:[1,0]
	v_pk_mul_f32 v[40:41], v[40:41], v[214:215] op_sel_hi:[1,0]
	v_pk_mul_f32 v[38:39], v[38:39], v[214:215] op_sel_hi:[1,0]
	v_pk_mul_f32 v[36:37], v[36:37], v[214:215] op_sel_hi:[1,0]
	v_pk_mul_f32 v[34:35], v[34:35], v[214:215] op_sel_hi:[1,0]
	v_mul_f32_e32 v211, v211, v214
